# phase-0 cast/norm loop: last four xor-shuffle steps of the sum-of-squares wave reduction done with DPP moves instead of ds_bpermute round trips
# speedup vs baseline: 1.0099x; 1.0024x over previous
; __device__ __forceinline__ float shx(float v, int mask, int lane) { return __int_as_float(__builtin_amdgcn_ds_bpermute((lane ^ mask) << 2, __float_as_int(v))); }
; __device__ __forceinline__ void norm_phase(const float* __restrict__ xin, const float* __restrict__ gain, const float* __restrict__ shift, const float* __restrict__ scale, bf16_t* __restrict__ H) {
;     ...
;         const float* xr = xin + (size_t)row * D;
;         f32x4 v[8]; float ss = 0.f;
; #pragma unroll
;         for (int i = 0; i < 8; ++i) { v[i] = *(const f32x4*)(xr + i * 256 + lane * 4); ss += v[i][0] * v[i][0] + v[i][1] * v[i][1] + v[i][2] * v[i][2] + v[i][3] * v[i][3]; }
; #pragma unroll
;         for (int o = 32; o > 0; o >>= 1) ss += shx(ss, o, lane);
.LBB0_39:
	v_lshl_add_u64 v[78:79], s[26:27], 0, v[128:129]
	v_add_co_u32_e32 v66, vcc, 0x11218000, v78
	s_mov_b32 s4, 0x11219000
	s_nop 0
	v_addc_co_u32_e32 v67, vcc, 0, v79, vcc
	flat_load_dwordx4 v[140:143], v[66:67]
	flat_load_dwordx4 v[74:77], v[66:67] offset:1024
	flat_load_dwordx4 v[70:73], v[66:67] offset:2048
	v_add_co_u32_e32 v78, vcc, s4, v78
	s_mov_b32 s4, 0x15218000
	s_nop 0
	v_addc_co_u32_e32 v79, vcc, 0, v79, vcc
	flat_load_dwordx4 v[66:69], v[66:67] offset:3072
	s_nop 0
	flat_load_dwordx4 v[90:93], v[78:79]
	flat_load_dwordx4 v[82:85], v[78:79] offset:1024
	flat_load_dwordx4 v[86:89], v[78:79] offset:2048
	s_nop 0
	flat_load_dwordx4 v[78:81], v[78:79] offset:3072
	v_add_u32_e32 v132, s88, v132
	v_lshl_add_u64 v[128:129], v[128:129], 0, s[12:13]
	s_waitcnt vmcnt(5)
	v_mul_f32_e32 v0, v141, v141
	v_mul_f32_e32 v144, v75, v75
	v_fmac_f32_e32 v0, v140, v140
	v_fmac_f32_e32 v144, v74, v74
	v_fmac_f32_e32 v0, v142, v142
	v_fmac_f32_e32 v144, v76, v76
	v_fmac_f32_e32 v0, v143, v143
	v_fmac_f32_e32 v144, v77, v77
	v_add_f32_e32 v0, v0, v144
	v_mul_f32_e32 v144, v71, v71
	v_fmac_f32_e32 v144, v70, v70
	v_fmac_f32_e32 v144, v72, v72
	v_fmac_f32_e32 v144, v73, v73
	v_add_f32_e32 v0, v0, v144
	s_waitcnt vmcnt(2)
	v_mov_b32_e32 v144, v91
	v_mul_f32_e32 v130, v67, v67
	v_fmac_f32_e32 v130, v66, v66
	v_fmac_f32_e32 v130, v68, v68
	v_fmac_f32_e32 v130, v69, v69
	v_mov_b32_e32 v145, v83
	v_add_f32_e32 v0, v0, v130
	v_mov_b32_e32 v130, v90
	v_mov_b32_e32 v131, v82
	v_pk_mul_f32 v[144:145], v[144:145], v[144:145]
	s_nop 0
	v_pk_fma_f32 v[130:131], v[130:131], v[130:131], v[144:145]
	v_mov_b32_e32 v144, v92
	v_mov_b32_e32 v145, v84
	v_pk_fma_f32 v[130:131], v[144:145], v[144:145], v[130:131]
	v_mov_b32_e32 v144, v93
	v_mov_b32_e32 v145, v85
	v_pk_fma_f32 v[130:131], v[144:145], v[144:145], v[130:131]
	s_nop 0
	v_add_f32_e32 v0, v0, v130
	v_add_f32_e32 v0, v0, v131
	s_waitcnt vmcnt(0) lgkmcnt(0)
	v_mov_b32_e32 v144, v87
	v_mov_b32_e32 v145, v79
	v_mov_b32_e32 v130, v86
	v_mov_b32_e32 v131, v78
	v_pk_mul_f32 v[144:145], v[144:145], v[144:145]
	s_nop 0
	v_pk_fma_f32 v[130:131], v[130:131], v[130:131], v[144:145]
	v_mov_b32_e32 v144, v88
	v_mov_b32_e32 v145, v80
	v_pk_fma_f32 v[130:131], v[144:145], v[144:145], v[130:131]
	v_mov_b32_e32 v144, v89
	v_mov_b32_e32 v145, v81
	v_pk_fma_f32 v[130:131], v[144:145], v[144:145], v[130:131]
	s_nop 0
	v_add_f32_e32 v0, v0, v130
	v_add_f32_e32 v0, v0, v131
	ds_bpermute_b32 v130, v133, v0
	s_waitcnt lgkmcnt(0)
	v_add_f32_e32 v0, v0, v130
	ds_bpermute_b32 v130, v134, v0
	s_waitcnt lgkmcnt(0)
	v_add_f32_e32 v0, v0, v130
	s_nop 1
	v_mov_b32_dpp v130, v0 row_shl:8 row_mask:0xf bank_mask:0x3
	v_mov_b32_dpp v130, v0 row_shr:8 row_mask:0xf bank_mask:0xc
	s_waitcnt lgkmcnt(0)
	v_add_f32_e32 v0, v0, v130
	s_nop 1
	v_mov_b32_dpp v130, v0 row_shl:4 row_mask:0xf bank_mask:0x5
	v_mov_b32_dpp v130, v0 row_shr:4 row_mask:0xf bank_mask:0xa
	s_waitcnt lgkmcnt(0)
	v_add_f32_e32 v0, v0, v130
	s_nop 1
	v_mov_b32_dpp v130, v0 quad_perm:[2,3,0,1] row_mask:0xf bank_mask:0xf
	s_waitcnt lgkmcnt(0)
	v_add_f32_e32 v0, v0, v130
	s_nop 1
	v_mov_b32_dpp v130, v0 quad_perm:[1,0,3,2] row_mask:0xf bank_mask:0xf
	s_waitcnt lgkmcnt(0)
; __device__ __forceinline__ unsigned pk2(float lo, float hi) { const f32v2_t v = {lo, hi}; return __builtin_bit_cast(unsigned, __builtin_convertvector(v, bf16v2_t)); }
; __device__ __forceinline__ void norm_phase(const float* __restrict__ xin, const float* __restrict__ gain, const float* __restrict__ shift, const float* __restrict__ scale, bf16_t* __restrict__ H) {
;     ...
;         const float inv = rsqrtf(ss * (1.f / D) + EPS);
; #pragma unroll
;         for (int i = 0; i < 8; ++i) {
;             const int c = i * 256 + lane * 4;
;             const f32x4 g = *(const f32x4*)(gain + c), sh = *(const f32x4*)(shift + c), sc = *(const f32x4*)(scale + c);
;             const f32x4 y = v[i] * inv * g * (1.f + sc) + sh;
;             u32x2 o = {pk2(y[0], y[1]), pk2(y[2], y[3])};
;             *(u32x2*)(H + (size_t)row * D + c) = o;
;         }
	v_add_f32_e32 v0, v0, v130
	v_fmamk_f32 v0, v0, 0x3a000000, v184
	v_cmp_gt_f32_e32 vcc, s90, v0
	v_mul_f32_e32 v130, 0x4b800000, v0
	s_nop 0
	v_cndmask_b32_e32 v0, v0, v130, vcc
	v_rsq_f32_e32 v0, v0
	s_nop 0
	v_mul_f32_e32 v130, 0x45800000, v0
	v_cndmask_b32_e32 v0, v0, v130, vcc
	v_pk_mul_f32 v[130:131], v[142:143], v[0:1] op_sel_hi:[1,0]
	v_pk_mul_f32 v[140:141], v[140:141], v[0:1] op_sel_hi:[1,0]
	v_pk_mul_f32 v[130:131], v[8:9], v[130:131]
	v_pk_mul_f32 v[140:141], v[6:7], v[140:141]
	v_pk_mul_f32 v[68:69], v[68:69], v[0:1] op_sel_hi:[1,0]
	v_pk_mul_f32 v[66:67], v[66:67], v[0:1] op_sel_hi:[1,0]
	v_pk_fma_f32 v[142:143], v[96:97], v[130:131], v[4:5]
	v_pk_fma_f32 v[130:131], v[98:99], v[140:141], v[2:3]
	v_lshl_add_u64 v[140:141], s[26:27], 0, v[94:95]
	v_pk_mul_f32 v[66:67], v[26:27], v[66:67]
	v_pk_mul_f32 v[68:69], v[28:29], v[68:69]
	v_add_co_u32_e32 v140, vcc, s4, v140
	v_pk_fma_f32 v[68:69], v[108:109], v[68:69], v[32:33]
	v_pk_fma_f32 v[66:67], v[110:111], v[66:67], v[30:31]
	v_addc_co_u32_e32 v141, vcc, 0, v141, vcc
	v_cvt_pk_bf16_f32 v66, v66, v67
	v_cvt_pk_bf16_f32 v67, v68, v69
	flat_store_dwordx2 v[140:141], v[66:67] offset:1536
	v_pk_mul_f32 v[66:67], v[92:93], v[0:1] op_sel_hi:[1,0]
	v_pk_mul_f32 v[68:69], v[90:91], v[0:1] op_sel_hi:[1,0]
	v_pk_mul_f32 v[66:67], v[48:49], v[66:67]
	v_pk_mul_f32 v[68:69], v[46:47], v[68:69]
	v_pk_fma_f32 v[66:67], v[112:113], v[66:67], v[36:37]
	v_pk_fma_f32 v[68:69], v[114:115], v[68:69], v[34:35]
	v_pk_mul_f32 v[76:77], v[76:77], v[0:1] op_sel_hi:[1,0]
	v_cvt_pk_bf16_f32 v68, v68, v69
	v_cvt_pk_bf16_f32 v69, v66, v67
	flat_store_dwordx2 v[140:141], v[68:69] offset:2048
	v_pk_mul_f32 v[66:67], v[84:85], v[0:1] op_sel_hi:[1,0]
	v_pk_mul_f32 v[68:69], v[82:83], v[0:1] op_sel_hi:[1,0]
	v_pk_mul_f32 v[66:67], v[52:53], v[66:67]
	v_pk_mul_f32 v[68:69], v[50:51], v[68:69]
	v_pk_fma_f32 v[66:67], v[116:117], v[66:67], v[40:41]
	v_pk_fma_f32 v[68:69], v[118:119], v[68:69], v[38:39]
	v_pk_mul_f32 v[74:75], v[74:75], v[0:1] op_sel_hi:[1,0]
	v_cvt_pk_bf16_f32 v68, v68, v69
	v_cvt_pk_bf16_f32 v69, v66, v67
	flat_store_dwordx2 v[140:141], v[68:69] offset:2560
	v_pk_mul_f32 v[66:67], v[88:89], v[0:1] op_sel_hi:[1,0]
	v_pk_mul_f32 v[68:69], v[86:87], v[0:1] op_sel_hi:[1,0]
	v_pk_mul_f32 v[66:67], v[56:57], v[66:67]
	v_pk_mul_f32 v[68:69], v[54:55], v[68:69]
	v_pk_fma_f32 v[66:67], v[120:121], v[66:67], v[44:45]
	v_pk_fma_f32 v[68:69], v[122:123], v[68:69], v[42:43]
	v_pk_mul_f32 v[72:73], v[72:73], v[0:1] op_sel_hi:[1,0]
	v_cvt_pk_bf16_f32 v68, v68, v69
	v_cvt_pk_bf16_f32 v69, v66, v67
	v_pk_mul_f32 v[70:71], v[70:71], v[0:1] op_sel_hi:[1,0]
	flat_store_dwordx2 v[140:141], v[68:69] offset:3072
	v_pk_mul_f32 v[66:67], v[80:81], v[0:1] op_sel_hi:[1,0]
	v_pk_mul_f32 v[68:69], v[78:79], v[0:1] op_sel_hi:[1,0]
	v_pk_mul_f32 v[74:75], v[10:11], v[74:75]
	v_pk_mul_f32 v[76:77], v[12:13], v[76:77]
	v_pk_mul_f32 v[70:71], v[22:23], v[70:71]
	v_pk_mul_f32 v[72:73], v[24:25], v[72:73]
	v_pk_mul_f32 v[68:69], v[58:59], v[68:69]
	v_pk_mul_f32 v[66:67], v[60:61], v[66:67]
	v_pk_fma_f32 v[76:77], v[100:101], v[76:77], v[16:17]
	v_pk_fma_f32 v[74:75], v[102:103], v[74:75], v[14:15]
	v_pk_fma_f32 v[72:73], v[104:105], v[72:73], v[20:21]
	v_pk_fma_f32 v[70:71], v[106:107], v[70:71], v[18:19]
	v_pk_fma_f32 v[66:67], v[124:125], v[66:67], v[64:65]
	v_pk_fma_f32 v[68:69], v[126:127], v[68:69], v[62:63]
	v_cmp_lt_i32_e32 vcc, s91, v132
	v_cvt_pk_bf16_f32 v130, v130, v131
	v_cvt_pk_bf16_f32 v131, v142, v143
	v_cvt_pk_bf16_f32 v74, v74, v75
	v_cvt_pk_bf16_f32 v75, v76, v77
	v_cvt_pk_bf16_f32 v70, v70, v71
	v_cvt_pk_bf16_f32 v71, v72, v73
	v_cvt_pk_bf16_f32 v68, v68, v69
	v_cvt_pk_bf16_f32 v69, v66, v67
	v_lshl_add_u64 v[94:95], v[94:95], 0, s[10:11]
	s_or_b64 s[2:3], vcc, s[2:3]
	flat_store_dwordx2 v[140:141], v[130:131]
	flat_store_dwordx2 v[140:141], v[74:75] offset:512
	flat_store_dwordx2 v[140:141], v[70:71] offset:1024
	flat_store_dwordx2 v[140:141], v[68:69] offset:3584
	s_andn2_b64 exec, exec, s[2:3]
	s_cbranch_execnz .LBB0_39
